# final rmsnorm: next-row prefetch with two register sets, scalar row addressing, DPP reduction
# speedup vs baseline: 1.0029x; 1.0029x over previous
.LBB0_263:
	s_andn2_b64 vcc, exec, s[4:5]
	s_cbranch_vccnz .LBB0_268
	v_mov_b32_e32 v5, v197
	v_readlane_b32 s0, v253, 6
	v_ashrrev_i32_e32 v1, 6, v5
	s_nop 0
	v_add_u32_e32 v4, s0, v1
	s_mov_b32 s0, 0x8000
	v_cmp_gt_i32_e32 vcc, s0, v4
	s_and_saveexec_b64 s[4:5], vcc
	v_readlane_b32 s3, v253, 7
	s_cbranch_execz .LBB0_267
	s_waitcnt vmcnt(0) lgkmcnt(0)
	v_readlane_b32 s6, v254, 41
	v_readlane_b32 s7, v254, 42
	v_readfirstlane_b32 s18, v4
	v_and_b32_e32 v7, 63, v197
	s_load_dwordx4 s[8:11], s[6:7], 0x110
	v_lshlrev_b32_e32 v6, 4, v7
	s_mov_b32 s50, 1
	s_waitcnt lgkmcnt(0)
	s_lshl_b32 s40, s18, 12
	s_add_u32 s24, s10, s40
	s_addc_u32 s25, s11, 0
	global_load_dwordx4 v[8:11], v6, s[24:25]
	global_load_dwordx4 v[12:15], v6, s[24:25] offset:1024
	global_load_dwordx4 v[16:19], v6, s[24:25] offset:2048
	global_load_dwordx4 v[20:23], v6, s[24:25] offset:3072
	global_load_dwordx4 v[88:91], v6, s[8:9]
	global_load_dwordx4 v[92:95], v6, s[8:9] offset:1024
	global_load_dwordx4 v[96:99], v6, s[8:9] offset:2048
	global_load_dwordx4 v[100:103], v6, s[8:9] offset:3072
.Lfn_loop:
	s_add_u32 s23, s18, s3
	s_cmp_lt_u32 s23, 0x8000
	s_cbranch_scc0 .Lfn_lastA
	s_lshl_b32 s40, s23, 12
	s_add_u32 s30, s10, s40
	s_addc_u32 s31, s11, 0
	global_load_dwordx4 v[104:107], v6, s[30:31]
	global_load_dwordx4 v[108:111], v6, s[30:31] offset:1024
	global_load_dwordx4 v[112:115], v6, s[30:31] offset:2048
	global_load_dwordx4 v[116:119], v6, s[30:31] offset:3072
	s_waitcnt vmcnt(8)
	v_pk_mul_f32 v[56:57], v[8:9], v[8:9]
	v_pk_mul_f32 v[58:59], v[10:11], v[10:11]
	v_pk_fma_f32 v[56:57], v[12:13], v[12:13], v[56:57]
	v_pk_fma_f32 v[58:59], v[14:15], v[14:15], v[58:59]
	v_pk_fma_f32 v[56:57], v[16:17], v[16:17], v[56:57]
	v_pk_fma_f32 v[58:59], v[18:19], v[18:19], v[58:59]
	v_pk_fma_f32 v[56:57], v[20:21], v[20:21], v[56:57]
	v_pk_fma_f32 v[58:59], v[22:23], v[22:23], v[58:59]
	v_pk_add_f32 v[56:57], v[56:57], v[58:59]
	s_nop 0
	v_add_f32_e32 v60, v56, v57
	s_nop 1
	v_add_f32_dpp v60, v60, v60 quad_perm:[1,0,3,2] row_mask:0xf bank_mask:0xf
	s_nop 1
	v_add_f32_dpp v60, v60, v60 quad_perm:[2,3,0,1] row_mask:0xf bank_mask:0xf
	s_nop 1
	v_add_f32_dpp v60, v60, v60 row_half_mirror row_mask:0xf bank_mask:0xf
	s_nop 1
	v_add_f32_dpp v60, v60, v60 row_mirror row_mask:0xf bank_mask:0xf
	s_nop 1
	v_readlane_b32 s60, v60, 0
	v_readlane_b32 s61, v60, 16
	v_readlane_b32 s62, v60, 32
	v_readlane_b32 s63, v60, 48
	v_mov_b32_e32 v60, s60
	s_nop 0
	v_add_f32_e32 v60, s61, v60
	v_add_f32_e32 v60, s62, v60
	v_add_f32_e32 v60, s63, v60
	v_fmamk_f32 v60, v60, 0x3a800000, v233
	v_rsq_f32_e32 v62, v60
	s_cmp_eq_u32 s50, 0
	s_cbranch_scc1 .Lfn_g1
	s_waitcnt vmcnt(4)
	s_mov_b32 s50, 0
.Lfn_g1:
	v_pk_mul_f32 v[8:9], v[8:9], v[62:63] op_sel_hi:[1,0]
	v_pk_mul_f32 v[10:11], v[10:11], v[62:63] op_sel_hi:[1,0]
	v_pk_mul_f32 v[12:13], v[12:13], v[62:63] op_sel_hi:[1,0]
	v_pk_mul_f32 v[14:15], v[14:15], v[62:63] op_sel_hi:[1,0]
	v_pk_mul_f32 v[16:17], v[16:17], v[62:63] op_sel_hi:[1,0]
	v_pk_mul_f32 v[18:19], v[18:19], v[62:63] op_sel_hi:[1,0]
	v_pk_mul_f32 v[20:21], v[20:21], v[62:63] op_sel_hi:[1,0]
	v_pk_mul_f32 v[22:23], v[22:23], v[62:63] op_sel_hi:[1,0]
	v_pk_mul_f32 v[8:9], v[8:9], v[88:89]
	v_pk_mul_f32 v[10:11], v[10:11], v[90:91]
	v_pk_mul_f32 v[12:13], v[12:13], v[92:93]
	v_pk_mul_f32 v[14:15], v[14:15], v[94:95]
	v_pk_mul_f32 v[16:17], v[16:17], v[96:97]
	v_pk_mul_f32 v[18:19], v[18:19], v[98:99]
	v_pk_mul_f32 v[20:21], v[20:21], v[100:101]
	v_pk_mul_f32 v[22:23], v[22:23], v[102:103]
	global_store_dwordx4 v6, v[8:11], s[24:25]
	global_store_dwordx4 v6, v[12:15], s[24:25] offset:1024
	global_store_dwordx4 v6, v[16:19], s[24:25] offset:2048
	global_store_dwordx4 v6, v[20:23], s[24:25] offset:3072
	s_add_u32 s18, s23, s3
	s_cmp_lt_u32 s18, 0x8000
	s_cbranch_scc0 .Lfn_lastB
	s_lshl_b32 s40, s18, 12
	s_add_u32 s24, s10, s40
	s_addc_u32 s25, s11, 0
	global_load_dwordx4 v[8:11], v6, s[24:25]
	global_load_dwordx4 v[12:15], v6, s[24:25] offset:1024
	global_load_dwordx4 v[16:19], v6, s[24:25] offset:2048
	global_load_dwordx4 v[20:23], v6, s[24:25] offset:3072
	s_waitcnt vmcnt(8)
	v_pk_mul_f32 v[56:57], v[104:105], v[104:105]
	v_pk_mul_f32 v[58:59], v[106:107], v[106:107]
	v_pk_fma_f32 v[56:57], v[108:109], v[108:109], v[56:57]
	v_pk_fma_f32 v[58:59], v[110:111], v[110:111], v[58:59]
	v_pk_fma_f32 v[56:57], v[112:113], v[112:113], v[56:57]
	v_pk_fma_f32 v[58:59], v[114:115], v[114:115], v[58:59]
	v_pk_fma_f32 v[56:57], v[116:117], v[116:117], v[56:57]
	v_pk_fma_f32 v[58:59], v[118:119], v[118:119], v[58:59]
	v_pk_add_f32 v[56:57], v[56:57], v[58:59]
	s_nop 0
	v_add_f32_e32 v60, v56, v57
	s_nop 1
	v_add_f32_dpp v60, v60, v60 quad_perm:[1,0,3,2] row_mask:0xf bank_mask:0xf
	s_nop 1
	v_add_f32_dpp v60, v60, v60 quad_perm:[2,3,0,1] row_mask:0xf bank_mask:0xf
	s_nop 1
	v_add_f32_dpp v60, v60, v60 row_half_mirror row_mask:0xf bank_mask:0xf
	s_nop 1
	v_add_f32_dpp v60, v60, v60 row_mirror row_mask:0xf bank_mask:0xf
	s_nop 1
	v_readlane_b32 s60, v60, 0
	v_readlane_b32 s61, v60, 16
	v_readlane_b32 s62, v60, 32
	v_readlane_b32 s63, v60, 48
	v_mov_b32_e32 v60, s60
	s_nop 0
	v_add_f32_e32 v60, s61, v60
	v_add_f32_e32 v60, s62, v60
	v_add_f32_e32 v60, s63, v60
	v_fmamk_f32 v60, v60, 0x3a800000, v233
	v_rsq_f32_e32 v62, v60
	s_nop 0
	v_pk_mul_f32 v[104:105], v[104:105], v[62:63] op_sel_hi:[1,0]
	v_pk_mul_f32 v[106:107], v[106:107], v[62:63] op_sel_hi:[1,0]
	v_pk_mul_f32 v[108:109], v[108:109], v[62:63] op_sel_hi:[1,0]
	v_pk_mul_f32 v[110:111], v[110:111], v[62:63] op_sel_hi:[1,0]
	v_pk_mul_f32 v[112:113], v[112:113], v[62:63] op_sel_hi:[1,0]
	v_pk_mul_f32 v[114:115], v[114:115], v[62:63] op_sel_hi:[1,0]
	v_pk_mul_f32 v[116:117], v[116:117], v[62:63] op_sel_hi:[1,0]
	v_pk_mul_f32 v[118:119], v[118:119], v[62:63] op_sel_hi:[1,0]
	v_pk_mul_f32 v[104:105], v[104:105], v[88:89]
	v_pk_mul_f32 v[106:107], v[106:107], v[90:91]
	v_pk_mul_f32 v[108:109], v[108:109], v[92:93]
	v_pk_mul_f32 v[110:111], v[110:111], v[94:95]
	v_pk_mul_f32 v[112:113], v[112:113], v[96:97]
	v_pk_mul_f32 v[114:115], v[114:115], v[98:99]
	v_pk_mul_f32 v[116:117], v[116:117], v[100:101]
	v_pk_mul_f32 v[118:119], v[118:119], v[102:103]
	global_store_dwordx4 v6, v[104:107], s[30:31]
	global_store_dwordx4 v6, v[108:111], s[30:31] offset:1024
	global_store_dwordx4 v6, v[112:115], s[30:31] offset:2048
	global_store_dwordx4 v6, v[116:119], s[30:31] offset:3072
	s_branch .Lfn_loop
.Lfn_lastA:
	s_waitcnt vmcnt(0)
	v_pk_mul_f32 v[56:57], v[8:9], v[8:9]
	v_pk_mul_f32 v[58:59], v[10:11], v[10:11]
	v_pk_fma_f32 v[56:57], v[12:13], v[12:13], v[56:57]
	v_pk_fma_f32 v[58:59], v[14:15], v[14:15], v[58:59]
	v_pk_fma_f32 v[56:57], v[16:17], v[16:17], v[56:57]
	v_pk_fma_f32 v[58:59], v[18:19], v[18:19], v[58:59]
	v_pk_fma_f32 v[56:57], v[20:21], v[20:21], v[56:57]
	v_pk_fma_f32 v[58:59], v[22:23], v[22:23], v[58:59]
	v_pk_add_f32 v[56:57], v[56:57], v[58:59]
	s_nop 0
	v_add_f32_e32 v60, v56, v57
	s_nop 1
	v_add_f32_dpp v60, v60, v60 quad_perm:[1,0,3,2] row_mask:0xf bank_mask:0xf
	s_nop 1
	v_add_f32_dpp v60, v60, v60 quad_perm:[2,3,0,1] row_mask:0xf bank_mask:0xf
	s_nop 1
	v_add_f32_dpp v60, v60, v60 row_half_mirror row_mask:0xf bank_mask:0xf
	s_nop 1
	v_add_f32_dpp v60, v60, v60 row_mirror row_mask:0xf bank_mask:0xf
	s_nop 1
	v_readlane_b32 s60, v60, 0
	v_readlane_b32 s61, v60, 16
	v_readlane_b32 s62, v60, 32
	v_readlane_b32 s63, v60, 48
	v_mov_b32_e32 v60, s60
	s_nop 0
	v_add_f32_e32 v60, s61, v60
	v_add_f32_e32 v60, s62, v60
	v_add_f32_e32 v60, s63, v60
	v_fmamk_f32 v60, v60, 0x3a800000, v233
	v_rsq_f32_e32 v62, v60
	s_nop 0
	v_pk_mul_f32 v[8:9], v[8:9], v[62:63] op_sel_hi:[1,0]
	v_pk_mul_f32 v[10:11], v[10:11], v[62:63] op_sel_hi:[1,0]
	v_pk_mul_f32 v[12:13], v[12:13], v[62:63] op_sel_hi:[1,0]
	v_pk_mul_f32 v[14:15], v[14:15], v[62:63] op_sel_hi:[1,0]
	v_pk_mul_f32 v[16:17], v[16:17], v[62:63] op_sel_hi:[1,0]
	v_pk_mul_f32 v[18:19], v[18:19], v[62:63] op_sel_hi:[1,0]
	v_pk_mul_f32 v[20:21], v[20:21], v[62:63] op_sel_hi:[1,0]
	v_pk_mul_f32 v[22:23], v[22:23], v[62:63] op_sel_hi:[1,0]
	v_pk_mul_f32 v[8:9], v[8:9], v[88:89]
	v_pk_mul_f32 v[10:11], v[10:11], v[90:91]
	v_pk_mul_f32 v[12:13], v[12:13], v[92:93]
	v_pk_mul_f32 v[14:15], v[14:15], v[94:95]
	v_pk_mul_f32 v[16:17], v[16:17], v[96:97]
	v_pk_mul_f32 v[18:19], v[18:19], v[98:99]
	v_pk_mul_f32 v[20:21], v[20:21], v[100:101]
	v_pk_mul_f32 v[22:23], v[22:23], v[102:103]
	global_store_dwordx4 v6, v[8:11], s[24:25]
	global_store_dwordx4 v6, v[12:15], s[24:25] offset:1024
	global_store_dwordx4 v6, v[16:19], s[24:25] offset:2048
	global_store_dwordx4 v6, v[20:23], s[24:25] offset:3072
	s_branch .Lfn_end
.Lfn_lastB:
	s_waitcnt vmcnt(0)
	v_pk_mul_f32 v[56:57], v[104:105], v[104:105]
	v_pk_mul_f32 v[58:59], v[106:107], v[106:107]
	v_pk_fma_f32 v[56:57], v[108:109], v[108:109], v[56:57]
	v_pk_fma_f32 v[58:59], v[110:111], v[110:111], v[58:59]
	v_pk_fma_f32 v[56:57], v[112:113], v[112:113], v[56:57]
	v_pk_fma_f32 v[58:59], v[114:115], v[114:115], v[58:59]
	v_pk_fma_f32 v[56:57], v[116:117], v[116:117], v[56:57]
	v_pk_fma_f32 v[58:59], v[118:119], v[118:119], v[58:59]
	v_pk_add_f32 v[56:57], v[56:57], v[58:59]
	s_nop 0
	v_add_f32_e32 v60, v56, v57
	s_nop 1
	v_add_f32_dpp v60, v60, v60 quad_perm:[1,0,3,2] row_mask:0xf bank_mask:0xf
	s_nop 1
	v_add_f32_dpp v60, v60, v60 quad_perm:[2,3,0,1] row_mask:0xf bank_mask:0xf
	s_nop 1
	v_add_f32_dpp v60, v60, v60 row_half_mirror row_mask:0xf bank_mask:0xf
	s_nop 1
	v_add_f32_dpp v60, v60, v60 row_mirror row_mask:0xf bank_mask:0xf
	s_nop 1
	v_readlane_b32 s60, v60, 0
	v_readlane_b32 s61, v60, 16
	v_readlane_b32 s62, v60, 32
	v_readlane_b32 s63, v60, 48
	v_mov_b32_e32 v60, s60
	s_nop 0
	v_add_f32_e32 v60, s61, v60
	v_add_f32_e32 v60, s62, v60
	v_add_f32_e32 v60, s63, v60
	v_fmamk_f32 v60, v60, 0x3a800000, v233
	v_rsq_f32_e32 v62, v60
	s_nop 0
	v_pk_mul_f32 v[104:105], v[104:105], v[62:63] op_sel_hi:[1,0]
	v_pk_mul_f32 v[106:107], v[106:107], v[62:63] op_sel_hi:[1,0]
	v_pk_mul_f32 v[108:109], v[108:109], v[62:63] op_sel_hi:[1,0]
	v_pk_mul_f32 v[110:111], v[110:111], v[62:63] op_sel_hi:[1,0]
	v_pk_mul_f32 v[112:113], v[112:113], v[62:63] op_sel_hi:[1,0]
	v_pk_mul_f32 v[114:115], v[114:115], v[62:63] op_sel_hi:[1,0]
	v_pk_mul_f32 v[116:117], v[116:117], v[62:63] op_sel_hi:[1,0]
	v_pk_mul_f32 v[118:119], v[118:119], v[62:63] op_sel_hi:[1,0]
	v_pk_mul_f32 v[104:105], v[104:105], v[88:89]
	v_pk_mul_f32 v[106:107], v[106:107], v[90:91]
	v_pk_mul_f32 v[108:109], v[108:109], v[92:93]
	v_pk_mul_f32 v[110:111], v[110:111], v[94:95]
	v_pk_mul_f32 v[112:113], v[112:113], v[96:97]
	v_pk_mul_f32 v[114:115], v[114:115], v[98:99]
	v_pk_mul_f32 v[116:117], v[116:117], v[100:101]
	v_pk_mul_f32 v[118:119], v[118:119], v[102:103]
	global_store_dwordx4 v6, v[104:107], s[30:31]
	global_store_dwordx4 v6, v[108:111], s[30:31] offset:1024
	global_store_dwordx4 v6, v[112:115], s[30:31] offset:2048
	global_store_dwordx4 v6, v[116:119], s[30:31] offset:3072
